# census: first xcd barrier's 16 census counter loads issued together (one wait) instead of 16 serial round trips
# speedup vs baseline: 1.0086x; 1.0025x over previous
;   __host__ __device__ __forceinline__ float* G() const { return (float*)(wsl() + OFF_G); }
;   __host__ __device__ __forceinline__ unsigned* bar() const { return (unsigned*)(wsl() + OFF_BAR); }
; __device__ __forceinline__ unsigned xb_ld(unsigned* p)              { return __hip_atomic_load(p, __ATOMIC_RELAXED, __HIP_MEMORY_SCOPE_AGENT); }
; __device__ __forceinline__ void xcd_barrier_complete(unsigned* bar, unsigned x, unsigned& nloc, unsigned& nx) {
;     const unsigned G = gridDim.x * gridDim.y * gridDim.z;
;     unsigned sum, cnt, mine, sp = 0u;
;     for (;;) {
;         sum = 0u; cnt = 0u; mine = 0u;
; #pragma unroll
;         for (unsigned j = 0; j < 16; ++j) { const unsigned c = xb_ld(&bar[XB_XCNT(j)]); sum += c; cnt += (c > 0u) ? 1u : 0u; mine = (j == x) ? c : mine; }
;         if (sum == G) break;
;         __builtin_amdgcn_s_sleep(1);
;         if ((++sp & 255u) == 0u) { if (xb_ld(&bar[XB_TMO])) break; if (sp > XB_SPIN_CAP) { atomicAdd(&bar[XB_TMO], 1u); break; } }
;     }
;     nloc = mine > 0u ? mine : 1u; nx = cnt > 0u ? cnt : 1u;
; }
.LBB0_1076:
	v_readlane_b32 s3, v255, 20
	s_mov_b64 s[6:7], -1
	s_waitcnt lgkmcnt(0)
	v_readlane_b32 s4, v254, 10
	v_readlane_b32 s5, v254, 11
	s_nop 4
	global_load_dword v0, v167, s[4:5] sc1
	v_readlane_b32 s4, v254, 12
	v_readlane_b32 s5, v254, 13
	s_nop 4
	global_load_dword v1, v167, s[4:5] sc1
	v_readlane_b32 s4, v254, 14
	v_readlane_b32 s5, v254, 15
	s_nop 4
	global_load_dword v2, v167, s[4:5] sc1
	v_readlane_b32 s4, v254, 16
	v_readlane_b32 s5, v254, 17
	s_nop 4
	global_load_dword v3, v167, s[4:5] sc1
	v_readlane_b32 s4, v254, 18
	v_readlane_b32 s5, v254, 19
	s_nop 4
	global_load_dword v4, v167, s[4:5] sc1
	v_readlane_b32 s4, v254, 20
	v_readlane_b32 s5, v254, 21
	s_nop 4
	global_load_dword v5, v167, s[4:5] sc1
	v_readlane_b32 s4, v254, 22
	v_readlane_b32 s5, v254, 23
	s_nop 4
	global_load_dword v6, v167, s[4:5] sc1
	v_readlane_b32 s4, v254, 24
	v_readlane_b32 s5, v254, 25
	s_nop 4
	global_load_dword v7, v167, s[4:5] sc1
	v_readlane_b32 s4, v254, 26
	v_readlane_b32 s5, v254, 27
	s_nop 4
	global_load_dword v8, v167, s[4:5] sc1
	v_readlane_b32 s4, v254, 28
	v_readlane_b32 s5, v254, 29
	s_nop 4
	global_load_dword v9, v167, s[4:5] sc1
	v_readlane_b32 s4, v254, 30
	v_readlane_b32 s5, v254, 31
	s_nop 4
	global_load_dword v10, v167, s[4:5] sc1
	v_readlane_b32 s4, v254, 32
	v_readlane_b32 s5, v254, 33
	s_nop 4
	global_load_dword v11, v167, s[4:5] sc1
	v_readlane_b32 s4, v254, 34
	v_readlane_b32 s5, v254, 35
	s_nop 4
	global_load_dword v12, v167, s[4:5] sc1
	v_readlane_b32 s4, v254, 36
	v_readlane_b32 s5, v254, 37
	s_nop 4
	global_load_dword v13, v167, s[4:5] sc1
	v_readlane_b32 s4, v254, 38
	v_readlane_b32 s5, v254, 39
	s_nop 4
	global_load_dword v14, v167, s[4:5] sc1
	v_readlane_b32 s4, v254, 40
	v_readlane_b32 s5, v254, 41
	s_nop 4
	global_load_dword v15, v167, s[4:5] sc1
	s_mov_b64 s[4:5], -1
	s_waitcnt vmcnt(0)
	v_add_u32_e32 v16, v1, v0
	v_add_u32_e32 v16, v16, v2
	v_add_u32_e32 v16, v16, v3
	v_add_u32_e32 v16, v16, v4
	v_add_u32_e32 v16, v16, v5
	v_add_u32_e32 v16, v16, v6
	v_add_u32_e32 v16, v16, v7
	v_add_u32_e32 v16, v16, v8
	v_add_u32_e32 v16, v16, v9
	v_add_u32_e32 v16, v16, v10
	v_add_u32_e32 v16, v16, v11
	v_add_u32_e32 v16, v16, v12
	v_add_u32_e32 v16, v16, v13
	v_add_u32_e32 v16, v16, v14
	v_add_u32_e32 v16, v16, v15
	v_cmp_eq_u32_e32 vcc, s3, v16
	s_cbranch_vccnz .LBB0_1075
	s_and_b32 s3, s2, 0xff
	s_cmp_eq_u32 s3, 0
	s_mov_b64 s[8:9], -1
	s_sleep 1
	s_cbranch_scc1 .LBB0_1080
	s_and_b64 vcc, exec, s[8:9]
	s_cbranch_vccz .LBB0_1075
